# LRU output epilogue loop: gate values prefetched one trip ahead (no store drain, no exposed load latency), the 16 LDS h-reads of a trip issued together instead of pairwise with waits
# baseline (speedup 1.0000x reference)
; __device__ __forceinline__ bf16_t f2bf(float f) { return (bf16_t)(cvt_pk_bf16(f, 0.f) & 0xffffu); }
; __device__ __forceinline__ float bf2f(bf16_t b) { return __uint_as_float(((unsigned)b) << 16); }
; __device__ __forceinline__ float sigmoidf_(float x) { return 1.0f / (1.0f + __expf(-x)); }
; template <bool FINAL>
; __device__ __forceinline__ void lru_item(const Ctx& C, int l, int item) {
;     ...
;         for (int s4 = 0; s4 < 4; ++s4) { const int tt = z ? 3 - s4 : s4;
;             const bf16_t* xrow = xc + (16 * tt + fr) * XCP + n * 64 + 8 * quad;
;             const bf16x8 xa0 = *(const bf16x8*)xrow, xa1 = *(const bf16x8*)(xrow + 32);
; #pragma unroll
;             for (int dt = 0; dt < 4; ++dt) {
;                 f32x4 Da = {0.f, 0.f, 0.f, 0.f}, Dx = {0.f, 0.f, 0.f, 0.f};
;                 Da = __builtin_amdgcn_mfma_f32_16x16x32_bf16(xa0, Bw[0][dt][0], Da, 0, 0, 0); Da = __builtin_amdgcn_mfma_f32_16x16x32_bf16(xa1, Bw[0][dt][1], Da, 0, 0, 0);
;                 Dx = __builtin_amdgcn_mfma_f32_16x16x32_bf16(xa0, Bw[1][dt][0], Dx, 0, 0, 0); Dx = __builtin_amdgcn_mfma_f32_16x16x32_bf16(xa1, Bw[1][dt][1], Dx, 0, 0, 0);
; #pragma unroll
;                 for (int r = 0; r < 4; ++r) { const int tloc = 4 * quad + r, d = 16 * dt + fr;
;                     const float rg = sigmoidf_(Da[r] + bav[dt]), ig = sigmoidf_(Dx[r] + bxv[dt]), la = -8.0f * rg * spv[dt], a = __expf(la);
;                     const float x = bf2f(xc[(16 * tt + tloc) * XCP + n * 64 + d]);
;                     Al[tloc * 68 + d] = a; Ul[tloc * 68 + d] = f2bf(sqrtf(fmaxf(1.0f - a * a, 0.f)) * ig * x); }
.LBB0_681:
	s_and_b64 s[0:1], s[4:5], exec
	s_cselect_b32 s0, s9, s51
	s_lshl_b32 s52, s0, 4
	v_or_b32_e32 v66, s52, v97
	v_mad_u64_u32 v[66:67], s[0:1], v66, s58, v[96:97]
	ds_read_b128 v[70:73], v66
	ds_read_b128 v[66:69], v66 offset:64
	s_add_i32 s9, s9, 1
	s_add_i32 s51, s51, -1
	s_waitcnt lgkmcnt(1)
	v_mfma_f32_16x16x32_bf16 v[74:77], v[70:73], v[0:3], 0
	s_waitcnt lgkmcnt(0)
	v_mfma_f32_16x16x32_bf16 v[74:77], v[66:69], v[16:19], v[74:77]
	v_mfma_f32_16x16x32_bf16 v[104:107], v[70:73], v[32:35], 0
	v_mfma_f32_16x16x32_bf16 v[174:177], v[66:69], v[48:51], v[104:107]
	s_nop 5
	v_fma_f32 v74, v74, s67, v64
	v_exp_f32_e32 v74, v74
	s_nop 0
	v_add_f32_e32 v74, 1.0, v74
	v_rcp_f32_e32 v74, v74
	v_fma_f32 v104, v174, s67, v162
	v_exp_f32_e32 v104, v104
	v_mul_f32_e32 v74, v163, v74
	v_add_f32_e32 v104, 1.0, v104
	v_exp_f32_e32 v74, v74
	ds_write_b32 v114, v74 offset:33792
	v_fma_f32 v74, -v74, v74, 1.0
	v_max_f32_e32 v74, 0, v74
	v_rcp_f32_e32 v104, v104
	v_or_b32_e32 v105, s52, v112
	v_mad_u64_u32 v[110:111], s[0:1], v105, s58, v[98:99]
	ds_read_u16 v105, v110
	s_waitcnt lgkmcnt(0)
	v_lshlrev_b32_e32 v105, 16, v105
	v_sqrt_f32_e32 v74, v74
	s_nop 0
	v_mul_f32_e32 v74, v104, v74
	v_mul_f32_e32 v74, v74, v105
	v_cvt_pk_bf16_f32 v74, v74, s0
	ds_write_b16 v87, v74 offset:38144
	v_fma_f32 v74, v75, s67, v64
	v_exp_f32_e32 v74, v74
	s_nop 0
	v_add_f32_e32 v74, 1.0, v74
	v_rcp_f32_e32 v74, v74
	v_fma_f32 v75, v175, s67, v162
	v_exp_f32_e32 v75, v75
	v_mul_f32_e32 v74, v163, v74
	v_add_f32_e32 v75, 1.0, v75
	v_exp_f32_e32 v74, v74
	ds_write_b32 v116, v74 offset:33792
	v_fma_f32 v74, -v74, v74, 1.0
	v_max_f32_e32 v74, 0, v74
	v_rcp_f32_e32 v75, v75
	v_or_b32_e32 v104, s52, v115
	v_mad_u64_u32 v[108:109], s[0:1], v104, s58, v[98:99]
	ds_read_u16 v104, v108
	s_waitcnt lgkmcnt(0)
	v_lshlrev_b32_e32 v104, 16, v104
	v_sqrt_f32_e32 v74, v74
	s_nop 0
	v_mul_f32_e32 v74, v75, v74
	v_mul_f32_e32 v74, v74, v104
	v_cvt_pk_bf16_f32 v74, v74, s0
	ds_write_b16 v144, v74 offset:38144
	v_fma_f32 v74, v76, s67, v64
	v_exp_f32_e32 v74, v74
	s_nop 0
	v_add_f32_e32 v74, 1.0, v74
	v_rcp_f32_e32 v74, v74
	v_fma_f32 v75, v176, s67, v162
	v_exp_f32_e32 v75, v75
	v_mul_f32_e32 v74, v163, v74
	v_add_f32_e32 v75, 1.0, v75
	v_exp_f32_e32 v74, v74
	ds_write_b32 v118, v74 offset:33792
	v_fma_f32 v74, -v74, v74, 1.0
	v_max_f32_e32 v74, 0, v74
	v_rcp_f32_e32 v75, v75
	v_or_b32_e32 v76, s52, v117
	v_mad_u64_u32 v[106:107], s[0:1], v76, s58, v[98:99]
	ds_read_u16 v76, v106
	s_waitcnt lgkmcnt(0)
	v_lshlrev_b32_e32 v76, 16, v76
	v_sqrt_f32_e32 v74, v74
	s_nop 0
	v_mul_f32_e32 v74, v75, v74
	v_mul_f32_e32 v74, v74, v76
	v_cvt_pk_bf16_f32 v74, v74, s0
	ds_write_b16 v145, v74 offset:38144
	v_fma_f32 v74, v77, s67, v64
	v_exp_f32_e32 v74, v74
	s_nop 0
	v_add_f32_e32 v74, 1.0, v74
	v_rcp_f32_e32 v74, v74
	v_fma_f32 v75, v177, s67, v162
	v_exp_f32_e32 v75, v75
	v_mul_f32_e32 v74, v163, v74
	v_add_f32_e32 v75, 1.0, v75
	v_exp_f32_e32 v74, v74
	v_mfma_f32_16x16x32_bf16 v[174:177], v[70:73], v[36:39], 0
	ds_write_b32 v120, v74 offset:33792
	v_fma_f32 v74, -v74, v74, 1.0
	v_max_f32_e32 v74, 0, v74
	v_rcp_f32_e32 v75, v75
	v_or_b32_e32 v76, s52, v119
	v_mad_u64_u32 v[104:105], s[0:1], v76, s58, v[98:99]
	ds_read_u16 v76, v104
	v_mfma_f32_16x16x32_bf16 v[174:177], v[66:69], v[52:55], v[174:177]
	s_waitcnt lgkmcnt(0)
	v_lshlrev_b32_e32 v76, 16, v76
	v_sqrt_f32_e32 v74, v74
	s_nop 0
	v_mul_f32_e32 v74, v75, v74
	v_mul_f32_e32 v74, v74, v76
	v_cvt_pk_bf16_f32 v74, v74, s0
	ds_write_b16 v146, v74 offset:38144
	v_mfma_f32_16x16x32_bf16 v[74:77], v[70:73], v[4:7], 0
	v_mfma_f32_16x16x32_bf16 v[74:77], v[66:69], v[20:23], v[74:77]
	s_nop 7
	v_fma_f32 v74, v74, s67, v164
	v_exp_f32_e32 v74, v74
	s_nop 0
	v_add_f32_e32 v74, 1.0, v74
	v_rcp_f32_e32 v74, v74
	v_fma_f32 v105, v174, s67, v165
	v_exp_f32_e32 v105, v105
	v_mul_f32_e32 v74, v166, v74
	v_add_f32_e32 v105, 1.0, v105
	v_exp_f32_e32 v74, v74
	ds_write_b32 v114, v74 offset:33856
	v_fma_f32 v74, -v74, v74, 1.0
	v_max_f32_e32 v74, 0, v74
	v_rcp_f32_e32 v105, v105
	ds_read_u16 v107, v110 offset:32
	s_waitcnt lgkmcnt(0)
	v_lshlrev_b32_e32 v107, 16, v107
	v_sqrt_f32_e32 v74, v74
	s_nop 0
	v_mul_f32_e32 v74, v105, v74
	v_mul_f32_e32 v74, v74, v107
	v_cvt_pk_bf16_f32 v74, v74, s0
	ds_write_b16 v121, v74 offset:38176
	v_fma_f32 v74, v75, s67, v164
	v_exp_f32_e32 v74, v74
	s_nop 0
	v_add_f32_e32 v74, 1.0, v74
	v_rcp_f32_e32 v74, v74
	v_fma_f32 v75, v175, s67, v165
	v_exp_f32_e32 v75, v75
	v_mul_f32_e32 v74, v166, v74
	v_add_f32_e32 v75, 1.0, v75
	v_exp_f32_e32 v74, v74
	ds_write_b32 v116, v74 offset:33856
	v_fma_f32 v74, -v74, v74, 1.0
	v_max_f32_e32 v74, 0, v74
	v_rcp_f32_e32 v75, v75
	ds_read_u16 v105, v108 offset:32
	s_waitcnt lgkmcnt(0)
	v_lshlrev_b32_e32 v105, 16, v105
	v_sqrt_f32_e32 v74, v74
	s_nop 0
	v_mul_f32_e32 v74, v75, v74
	v_mul_f32_e32 v74, v74, v105
	v_cvt_pk_bf16_f32 v74, v74, s0
	ds_write_b16 v122, v74 offset:38176
	v_fma_f32 v74, v76, s67, v164
	v_exp_f32_e32 v74, v74
	s_nop 0
	v_add_f32_e32 v74, 1.0, v74
	v_rcp_f32_e32 v74, v74
	v_fma_f32 v75, v176, s67, v165
	v_exp_f32_e32 v75, v75
	v_mul_f32_e32 v74, v166, v74
	v_add_f32_e32 v75, 1.0, v75
	v_exp_f32_e32 v74, v74
	ds_write_b32 v118, v74 offset:33856
	v_fma_f32 v74, -v74, v74, 1.0
	v_max_f32_e32 v74, 0, v74
	v_rcp_f32_e32 v75, v75
	ds_read_u16 v76, v106 offset:32
	s_waitcnt lgkmcnt(0)
; __device__ __forceinline__ bf16_t f2bf(float f) { return (bf16_t)(cvt_pk_bf16(f, 0.f) & 0xffffu); }
; __device__ __forceinline__ float bf2f(bf16_t b) { return __uint_as_float(((unsigned)b) << 16); }
; __device__ __forceinline__ float sigmoidf_(float x) { return 1.0f / (1.0f + __expf(-x)); }
; template <bool FINAL>
; __device__ __forceinline__ void lru_item(const Ctx& C, int l, int item) {
;     ...
;             for (int dt = 0; dt < 4; ++dt) {
;                 f32x4 Da = {0.f, 0.f, 0.f, 0.f}, Dx = {0.f, 0.f, 0.f, 0.f};
;                 Da = __builtin_amdgcn_mfma_f32_16x16x32_bf16(xa0, Bw[0][dt][0], Da, 0, 0, 0); Da = __builtin_amdgcn_mfma_f32_16x16x32_bf16(xa1, Bw[0][dt][1], Da, 0, 0, 0);
;                 Dx = __builtin_amdgcn_mfma_f32_16x16x32_bf16(xa0, Bw[1][dt][0], Dx, 0, 0, 0); Dx = __builtin_amdgcn_mfma_f32_16x16x32_bf16(xa1, Bw[1][dt][1], Dx, 0, 0, 0);
; #pragma unroll
;                 for (int r = 0; r < 4; ++r) { const int tloc = 4 * quad + r, d = 16 * dt + fr;
;                     const float rg = sigmoidf_(Da[r] + bav[dt]), ig = sigmoidf_(Dx[r] + bxv[dt]), la = -8.0f * rg * spv[dt], a = __expf(la);
;                     const float x = bf2f(xc[(16 * tt + tloc) * XCP + n * 64 + d]);
;                     Al[tloc * 68 + d] = a; Ul[tloc * 68 + d] = f2bf(sqrtf(fmaxf(1.0f - a * a, 0.f)) * ig * x); }
	v_lshlrev_b32_e32 v76, 16, v76
	v_sqrt_f32_e32 v74, v74
	s_nop 0
	v_mul_f32_e32 v74, v75, v74
	v_mul_f32_e32 v74, v74, v76
	v_cvt_pk_bf16_f32 v74, v74, s0
	ds_write_b16 v123, v74 offset:38176
	v_fma_f32 v74, v77, s67, v164
	v_exp_f32_e32 v74, v74
	s_nop 0
	v_add_f32_e32 v74, 1.0, v74
	v_rcp_f32_e32 v74, v74
	v_fma_f32 v75, v177, s67, v165
	v_exp_f32_e32 v75, v75
	v_mul_f32_e32 v74, v166, v74
	v_add_f32_e32 v75, 1.0, v75
	v_exp_f32_e32 v74, v74
	v_mfma_f32_16x16x32_bf16 v[174:177], v[70:73], v[40:43], 0
	ds_write_b32 v120, v74 offset:33856
	v_fma_f32 v74, -v74, v74, 1.0
	v_max_f32_e32 v74, 0, v74
	v_rcp_f32_e32 v75, v75
	ds_read_u16 v76, v104 offset:32
	v_mfma_f32_16x16x32_bf16 v[174:177], v[66:69], v[56:59], v[174:177]
	s_waitcnt lgkmcnt(0)
	v_lshlrev_b32_e32 v76, 16, v76
	v_sqrt_f32_e32 v74, v74
	s_nop 0
	v_mul_f32_e32 v74, v75, v74
	v_mul_f32_e32 v74, v74, v76
	v_cvt_pk_bf16_f32 v74, v74, s0
	ds_write_b16 v124, v74 offset:38176
	v_mfma_f32_16x16x32_bf16 v[74:77], v[70:73], v[8:11], 0
	v_mfma_f32_16x16x32_bf16 v[74:77], v[66:69], v[24:27], v[74:77]
	s_nop 7
	v_fma_f32 v74, v74, s67, v167
	v_exp_f32_e32 v74, v74
	s_nop 0
	v_add_f32_e32 v74, 1.0, v74
	v_rcp_f32_e32 v74, v74
	v_fma_f32 v105, v174, s67, v168
	v_exp_f32_e32 v105, v105
	v_mul_f32_e32 v74, v169, v74
	v_add_f32_e32 v105, 1.0, v105
	v_exp_f32_e32 v74, v74
	ds_write_b32 v114, v74 offset:33920
	v_fma_f32 v74, -v74, v74, 1.0
	v_max_f32_e32 v74, 0, v74
	v_rcp_f32_e32 v105, v105
	ds_read_u16 v107, v110 offset:64
	s_waitcnt lgkmcnt(0)
	v_lshlrev_b32_e32 v107, 16, v107
	v_sqrt_f32_e32 v74, v74
	s_nop 0
	v_mul_f32_e32 v74, v105, v74
	v_mul_f32_e32 v74, v74, v107
	v_cvt_pk_bf16_f32 v74, v74, s0
	ds_write_b16 v121, v74 offset:38208
	v_fma_f32 v74, v75, s67, v167
	v_exp_f32_e32 v74, v74
	s_nop 0
	v_add_f32_e32 v74, 1.0, v74
	v_rcp_f32_e32 v74, v74
	v_fma_f32 v75, v175, s67, v168
	v_exp_f32_e32 v75, v75
	v_mul_f32_e32 v74, v169, v74
	v_add_f32_e32 v75, 1.0, v75
	v_exp_f32_e32 v74, v74
	ds_write_b32 v116, v74 offset:33920
	v_fma_f32 v74, -v74, v74, 1.0
	v_max_f32_e32 v74, 0, v74
	v_rcp_f32_e32 v75, v75
	ds_read_u16 v105, v108 offset:64
	s_waitcnt lgkmcnt(0)
	v_lshlrev_b32_e32 v105, 16, v105
	v_sqrt_f32_e32 v74, v74
	s_nop 0
	v_mul_f32_e32 v74, v75, v74
	v_mul_f32_e32 v74, v74, v105
	v_cvt_pk_bf16_f32 v74, v74, s0
	ds_write_b16 v122, v74 offset:38208
	v_fma_f32 v74, v76, s67, v167
	v_exp_f32_e32 v74, v74
	s_nop 0
	v_add_f32_e32 v74, 1.0, v74
	v_rcp_f32_e32 v74, v74
	v_fma_f32 v75, v176, s67, v168
	v_exp_f32_e32 v75, v75
	v_mul_f32_e32 v74, v169, v74
	v_add_f32_e32 v75, 1.0, v75
	v_exp_f32_e32 v74, v74
	ds_write_b32 v118, v74 offset:33920
	v_fma_f32 v74, -v74, v74, 1.0
	v_max_f32_e32 v74, 0, v74
	v_rcp_f32_e32 v75, v75
	ds_read_u16 v76, v106 offset:64
	s_waitcnt lgkmcnt(0)
	v_lshlrev_b32_e32 v76, 16, v76
	v_sqrt_f32_e32 v74, v74
	s_nop 0
	v_mul_f32_e32 v74, v75, v74
	v_mul_f32_e32 v74, v74, v76
	v_cvt_pk_bf16_f32 v74, v74, s0
	ds_write_b16 v123, v74 offset:38208
	v_fma_f32 v74, v77, s67, v167
	v_exp_f32_e32 v74, v74
	s_nop 0
	v_add_f32_e32 v74, 1.0, v74
	v_rcp_f32_e32 v74, v74
	v_fma_f32 v75, v177, s67, v168
	v_exp_f32_e32 v75, v75
	v_mul_f32_e32 v74, v169, v74
	v_add_f32_e32 v75, 1.0, v75
	v_exp_f32_e32 v74, v74
	ds_write_b32 v120, v74 offset:33920
	v_fma_f32 v74, -v74, v74, 1.0
	v_max_f32_e32 v74, 0, v74
	v_rcp_f32_e32 v75, v75
	ds_read_u16 v76, v104 offset:64
	s_waitcnt lgkmcnt(0)
	v_lshlrev_b32_e32 v76, 16, v76
	v_sqrt_f32_e32 v74, v74
	s_nop 0
	v_mul_f32_e32 v74, v75, v74
	v_mul_f32_e32 v74, v74, v76
	v_cvt_pk_bf16_f32 v74, v74, s0
	ds_write_b16 v124, v74 offset:38208
	v_mfma_f32_16x16x32_bf16 v[74:77], v[70:73], v[12:15], 0
	v_mfma_f32_16x16x32_bf16 v[74:77], v[66:69], v[28:31], v[74:77]
	v_mfma_f32_16x16x32_bf16 v[70:73], v[70:73], v[44:47], 0
	v_mfma_f32_16x16x32_bf16 v[66:69], v[66:69], v[60:63], v[70:73]
	s_waitcnt vmcnt(2)
	s_nop 5
	v_fma_f32 v70, v74, s67, v170
	v_exp_f32_e32 v70, v70
	s_waitcnt vmcnt(1)
	v_fma_f32 v66, v66, s67, v171
	v_exp_f32_e32 v66, v66
	v_add_f32_e32 v70, 1.0, v70
	v_add_f32_e32 v66, 1.0, v66
	v_fma_f32 v67, v67, s67, v171
	v_rcp_f32_e32 v70, v70
	s_nop 0
	v_mul_f32_e32 v70, v172, v70
	v_exp_f32_e32 v70, v70
	ds_write_b32 v114, v70 offset:33984
	v_fma_f32 v70, -v70, v70, 1.0
	v_max_f32_e32 v70, 0, v70
	v_rcp_f32_e32 v66, v66
	ds_read_u16 v71, v110 offset:96
	v_exp_f32_e32 v67, v67
	s_waitcnt lgkmcnt(0)
	v_lshlrev_b32_e32 v71, 16, v71
	v_add_f32_e32 v67, 1.0, v67
	v_sqrt_f32_e32 v70, v70
	s_nop 0
	v_mul_f32_e32 v66, v66, v70
	v_mul_f32_e32 v66, v66, v71
	v_cvt_pk_bf16_f32 v66, v66, s0
	ds_write_b16 v121, v66 offset:38240
	v_fma_f32 v66, v75, s67, v170
	v_exp_f32_e32 v66, v66
	s_nop 0
	v_add_f32_e32 v66, 1.0, v66
	v_rcp_f32_e32 v66, v66
	s_nop 0
	v_mul_f32_e32 v66, v172, v66
	v_exp_f32_e32 v66, v66
	ds_write_b32 v116, v66 offset:33984
	v_fma_f32 v66, -v66, v66, 1.0
	v_max_f32_e32 v66, 0, v66
	v_rcp_f32_e32 v67, v67
	ds_read_u16 v70, v108 offset:96
	s_waitcnt lgkmcnt(0)
	v_lshlrev_b32_e32 v70, 16, v70
	v_sqrt_f32_e32 v66, v66
	s_nop 0
	v_mul_f32_e32 v66, v67, v66
	v_mul_f32_e32 v66, v66, v70
	v_cvt_pk_bf16_f32 v66, v66, s0
	ds_write_b16 v122, v66 offset:38240
	v_fma_f32 v66, v76, s67, v170
	v_exp_f32_e32 v66, v66
	s_nop 0
	v_add_f32_e32 v66, 1.0, v66
	v_rcp_f32_e32 v66, v66
	v_fma_f32 v67, v68, s67, v171
	v_exp_f32_e32 v67, v67
	v_mul_f32_e32 v66, v172, v66
	v_add_f32_e32 v67, 1.0, v67
	v_exp_f32_e32 v66, v66
	ds_write_b32 v118, v66 offset:33984
	v_fma_f32 v66, -v66, v66, 1.0
	v_max_f32_e32 v66, 0, v66
	v_rcp_f32_e32 v67, v67
	ds_read_u16 v68, v106 offset:96
	s_waitcnt lgkmcnt(0)
; __device__ __forceinline__ bf16_t f2bf(float f) { return (bf16_t)(cvt_pk_bf16(f, 0.f) & 0xffffu); }
; __device__ __forceinline__ float bf2f(bf16_t b) { return __uint_as_float(((unsigned)b) << 16); }
; __device__ __forceinline__ void wave_lds_fence() { asm volatile("s_waitcnt lgkmcnt(0)" ::: "memory"); __builtin_amdgcn_wave_barrier(); }
;     __device__ __forceinline__ bf16_t* bfp(size_t off) const { return (bf16_t*)(ws + off); }
;     __device__ __forceinline__ float* fp(size_t off) const { return (float*)(ws + off); }
; template <bool FINAL>
; __device__ __forceinline__ void lru_item(const Ctx& C, int l, int item) {
;     ...
;             for (int j = 0; j < 16; ++j) { const int tloc = z ? 15 - j : j;
;                 const float a = Al[tloc * 68 + lane], u = bf2f(Ul[tloc * 68 + lane]);
;                 h = fmaf(a, h, u); Ap *= a;
;                 if (FINAL) Hz[(16 * tt + tloc) * 256 + n * 64 + lane] = f2bf(h); }
;             wave_lds_fence();
;         }
;         if (!FINAL) { C.fp(OFF_CARA)[cidx] = Ap; C.fp(OFF_CARH)[cidx] = h; }
;     }
;     if (FINAL) {
;         __syncthreads();
;         int ch = tid & 255; asm volatile("" : "+v"(ch)); const int zz = tid >> 8;
;         const bf16_t* gp = pb + (size_t)(b * SEQ + c * 64) * 512 + 256 + ch; bf16_t* yb = C.bfp(OFF_YB) + (size_t)(b * SEQ + c * 64) * 256 + ch;
; #pragma unroll 1
;         for (int k8 = 0; k8 < 4; ++k8) { bf16_t gv_[8];
; #pragma unroll
;             for (int k = 0; k < 8; ++k) gv_[k] = gp[(size_t)(zz * 32 + k8 * 8 + k) * 512];
	v_lshlrev_b32_e32 v68, 16, v68
	v_sqrt_f32_e32 v66, v66
	s_nop 0
	v_mul_f32_e32 v66, v67, v66
	v_mul_f32_e32 v66, v66, v68
	v_cvt_pk_bf16_f32 v66, v66, s0
	ds_write_b16 v123, v66 offset:38240
	v_fma_f32 v66, v77, s67, v170
	v_exp_f32_e32 v66, v66
	s_nop 0
	v_add_f32_e32 v66, 1.0, v66
	v_rcp_f32_e32 v66, v66
	v_fma_f32 v67, v69, s67, v171
	v_exp_f32_e32 v67, v67
	v_mul_f32_e32 v66, v172, v66
	v_add_f32_e32 v67, 1.0, v67
	v_exp_f32_e32 v66, v66
	ds_write_b32 v120, v66 offset:33984
	v_fma_f32 v66, -v66, v66, 1.0
	v_max_f32_e32 v66, 0, v66
	v_rcp_f32_e32 v67, v67
	ds_read_u16 v68, v104 offset:96
	s_waitcnt lgkmcnt(0)
	v_lshlrev_b32_e32 v68, 16, v68
	v_sqrt_f32_e32 v66, v66
	s_nop 0
	v_mul_f32_e32 v66, v67, v66
	v_mul_f32_e32 v66, v66, v68
	v_cvt_pk_bf16_f32 v66, v66, s0
	ds_write_b16 v124, v66 offset:38240
	s_waitcnt lgkmcnt(0)
	ds_read_b32 v67, v113 offset:33792
	ds_read_u16 v66, v125 offset:38144
	s_waitcnt lgkmcnt(0)
	v_lshlrev_b32_e32 v66, 16, v66
	s_waitcnt vmcnt(0)
	v_fmac_f32_e32 v66, v67, v173
	v_cvt_pk_bf16_f32 v67, v66, s0
	s_or_b32 s0, s52, s13
	v_lshl_add_u32 v68, s0, 9, v141
	ds_write_b16 v68, v67
	ds_read_b32 v68, v126 offset:33792
	ds_read_u16 v67, v147 offset:38144
	s_waitcnt lgkmcnt(0)
	v_lshlrev_b32_e32 v67, 16, v67
	v_fmac_f32_e32 v67, v68, v66
	v_cvt_pk_bf16_f32 v66, v67, s0
	s_or_b32 s0, s52, s14
	v_lshl_add_u32 v68, s0, 9, v141
	ds_write_b16 v68, v66
	ds_read_b32 v66, v127 offset:33792
	ds_read_u16 v68, v148 offset:38144
	s_waitcnt lgkmcnt(0)
	v_lshlrev_b32_e32 v68, 16, v68
	v_fmac_f32_e32 v68, v66, v67
	v_cvt_pk_bf16_f32 v66, v68, s0
	s_or_b32 s0, s52, s15
	v_lshl_add_u32 v67, s0, 9, v141
	ds_write_b16 v67, v66
	ds_read_b32 v66, v128 offset:33792
	ds_read_u16 v67, v149 offset:38144
	s_waitcnt lgkmcnt(0)
	v_lshlrev_b32_e32 v67, 16, v67
	v_fmac_f32_e32 v67, v66, v68
	v_cvt_pk_bf16_f32 v66, v67, s0
	s_or_b32 s0, s52, s16
	v_lshl_add_u32 v68, s0, 9, v141
	ds_write_b16 v68, v66
	ds_read_b32 v66, v129 offset:33792
	ds_read_u16 v68, v150 offset:38144
	s_waitcnt lgkmcnt(0)
	v_lshlrev_b32_e32 v68, 16, v68
	v_fmac_f32_e32 v68, v66, v67
	v_cvt_pk_bf16_f32 v66, v68, s0
	s_or_b32 s0, s52, s17
	v_lshl_add_u32 v67, s0, 9, v141
	ds_write_b16 v67, v66
	ds_read_b32 v66, v130 offset:33792
	ds_read_u16 v67, v151 offset:38144
	s_waitcnt lgkmcnt(0)
	v_lshlrev_b32_e32 v67, 16, v67
	v_fmac_f32_e32 v67, v66, v68
	v_cvt_pk_bf16_f32 v66, v67, s0
	s_or_b32 s0, s52, s18
	v_lshl_add_u32 v68, s0, 9, v141
	ds_write_b16 v68, v66
	ds_read_b32 v66, v131 offset:33792
	ds_read_u16 v68, v152 offset:38144
	s_waitcnt lgkmcnt(0)
	v_lshlrev_b32_e32 v68, 16, v68
	v_fmac_f32_e32 v68, v66, v67
	v_cvt_pk_bf16_f32 v66, v68, s0
	s_or_b32 s0, s52, s19
	v_lshl_add_u32 v67, s0, 9, v141
	ds_write_b16 v67, v66
	ds_read_b32 v66, v132 offset:33792
	ds_read_u16 v67, v153 offset:38144
	s_waitcnt lgkmcnt(0)
	v_lshlrev_b32_e32 v67, 16, v67
	v_fmac_f32_e32 v67, v66, v68
	v_cvt_pk_bf16_f32 v66, v67, s0
	s_or_b32 s0, s52, s20
	v_lshl_add_u32 v68, s0, 9, v141
	ds_write_b16 v68, v66
	ds_read_b32 v66, v133 offset:33792
	ds_read_u16 v68, v154 offset:38144
	s_waitcnt lgkmcnt(0)
	v_lshlrev_b32_e32 v68, 16, v68
	v_fmac_f32_e32 v68, v66, v67
	v_cvt_pk_bf16_f32 v66, v68, s0
	s_or_b32 s0, s52, s21
	v_lshl_add_u32 v67, s0, 9, v141
	ds_write_b16 v67, v66
	ds_read_b32 v66, v134 offset:33792
	ds_read_u16 v67, v155 offset:38144
	s_waitcnt lgkmcnt(0)
	v_lshlrev_b32_e32 v67, 16, v67
	v_fmac_f32_e32 v67, v66, v68
	v_cvt_pk_bf16_f32 v66, v67, s0
	s_or_b32 s0, s52, s36
	v_lshl_add_u32 v68, s0, 9, v141
	ds_write_b16 v68, v66
	ds_read_b32 v66, v135 offset:33792
	ds_read_u16 v68, v156 offset:38144
	s_waitcnt lgkmcnt(0)
	v_lshlrev_b32_e32 v68, 16, v68
	v_fmac_f32_e32 v68, v66, v67
	v_cvt_pk_bf16_f32 v66, v68, s0
	s_or_b32 s0, s52, s38
	v_lshl_add_u32 v67, s0, 9, v141
	ds_write_b16 v67, v66
	ds_read_b32 v66, v136 offset:33792
	ds_read_u16 v67, v157 offset:38144
	s_waitcnt lgkmcnt(0)
	v_lshlrev_b32_e32 v67, 16, v67
	v_fmac_f32_e32 v67, v66, v68
	v_cvt_pk_bf16_f32 v66, v67, s0
	s_or_b32 s0, s52, s39
	v_lshl_add_u32 v68, s0, 9, v141
	ds_write_b16 v68, v66
	ds_read_b32 v66, v137 offset:33792
	ds_read_u16 v68, v158 offset:38144
	s_waitcnt lgkmcnt(0)
	v_lshlrev_b32_e32 v68, 16, v68
	v_fmac_f32_e32 v68, v66, v67
	v_cvt_pk_bf16_f32 v66, v68, s0
	s_or_b32 s0, s52, s42
	v_lshl_add_u32 v67, s0, 9, v141
	ds_write_b16 v67, v66
	ds_read_b32 v66, v138 offset:33792
	ds_read_u16 v67, v159 offset:38144
	s_waitcnt lgkmcnt(0)
	v_lshlrev_b32_e32 v67, 16, v67
	v_fmac_f32_e32 v67, v66, v68
	v_cvt_pk_bf16_f32 v66, v67, s0
	s_or_b32 s0, s52, s43
	v_lshl_add_u32 v68, s0, 9, v141
	ds_write_b16 v68, v66
	ds_read_b32 v68, v139 offset:33792
	ds_read_u16 v66, v160 offset:38144
	s_waitcnt lgkmcnt(0)
	v_lshlrev_b32_e32 v66, 16, v66
	v_fmac_f32_e32 v66, v68, v67
	v_cvt_pk_bf16_f32 v67, v66, s0
	s_or_b32 s0, s52, s44
	v_lshl_add_u32 v68, s0, 9, v141
	ds_write_b16 v68, v67
	ds_read_b32 v67, v140 offset:33792
	ds_read_u16 v68, v161 offset:38144
	s_waitcnt lgkmcnt(0)
	v_lshlrev_b32_e32 v173, 16, v68
	v_fmac_f32_e32 v173, v67, v66
	v_cvt_pk_bf16_f32 v66, v173, s0
	s_or_b32 s0, s52, s45
	v_lshl_add_u32 v67, s0, 9, v141
	ds_write_b16 v67, v66
	s_waitcnt lgkmcnt(0)
	s_cmp_eq_u32 s9, 4
	s_cbranch_scc0 .LBB0_681
	s_add_i32 s0, s8, s49
	s_ashr_i32 s1, s0, 31
	v_mov_b32_e32 v4, v99
	s_lshl_b64 s[8:9], s[0:1], 10
	s_lshl_b64 s[0:1], s[0:1], 9
	s_waitcnt lgkmcnt(0)
	s_barrier
	v_lshl_add_u64 v[0:1], v[100:101], 0, s[8:9]
	v_ashrrev_i32_e32 v5, 31, v4
	v_lshl_add_u64 v[2:3], v[102:103], 0, s[0:1]
	v_lshl_add_u32 v8, v4, 1, v143
	v_lshlrev_b64 v[4:5], 1, v[4:5]
	s_mov_b32 s0, 0
	v_lshl_add_u64 v[10:11], v[0:1], 0, v[4:5]
	s_mov_b32 s1, 0xc001000
	v_add_co_u32_e32 v12, vcc, 0xc000000, v10
	s_nop 1
	v_addc_co_u32_e32 v13, vcc, 0, v11, vcc
	v_add_co_u32_e32 v10, vcc, s1, v10
	s_nop 1
	v_addc_co_u32_e32 v11, vcc, 0, v11, vcc
	global_load_ushort v24, v[12:13], off offset:512
	global_load_ushort v25, v[12:13], off offset:1536
	global_load_ushort v26, v[12:13], off offset:2560
	global_load_ushort v27, v[12:13], off offset:3584
	global_load_ushort v28, v[10:11], off offset:512
	global_load_ushort v29, v[10:11], off offset:1536
	global_load_ushort v30, v[10:11], off offset:2560
	global_load_ushort v31, v[10:11], off offset:3584
; __device__ __forceinline__ bf16_t f2bf(float f) { return (bf16_t)(cvt_pk_bf16(f, 0.f) & 0xffffu); }
; __device__ __forceinline__ float bf2f(bf16_t b) { return __uint_as_float(((unsigned)b) << 16); }
; __device__ __forceinline__ float geluf_(float x) { const float y = 0.7978845608028654f * (x + 0.044715f * x * x * x); const float t = 1.0f - 2.0f / (1.0f + __expf(2.0f * y)); return 0.5f * x * (1.0f + t); }
;     __device__ __forceinline__ bf16_t* bfp(size_t off) const { return (bf16_t*)(ws + off); }
; template <bool FINAL>
; __device__ __forceinline__ void lru_item(const Ctx& C, int l, int item) {
;     ...
;         int ch = tid & 255; asm volatile("" : "+v"(ch)); const int zz = tid >> 8;
;         const bf16_t* gp = pb + (size_t)(b * SEQ + c * 64) * 512 + 256 + ch; bf16_t* yb = C.bfp(OFF_YB) + (size_t)(b * SEQ + c * 64) * 256 + ch;
; #pragma unroll 1
;         for (int k8 = 0; k8 < 4; ++k8) { bf16_t gv_[8];
; #pragma unroll
;             for (int k = 0; k < 8; ++k) gv_[k] = gp[(size_t)(zz * 32 + k8 * 8 + k) * 512];
; #pragma unroll
;             for (int k = 0; k < 8; ++k) { const int tl = zz * 32 + k8 * 8 + k; const float hs = bf2f(H0[tl * 256 + ch]) + bf2f(H1[tl * 256 + ch]);
;                 yb[(size_t)tl * 256] = f2bf(hs * geluf_(bf2f(gv_[k]))); } }
.LBB0_683:
	v_add_u32_e32 v9, s0, v8
	v_add_u32_e32 v23, 0x15000, v9
	v_lshl_add_u64 v[0:1], v[0:1], 0, s[30:31]
	v_lshl_add_u64 v[10:11], v[0:1], 0, v[4:5]
	s_mov_b32 s1, 0xc001000
	v_add_co_u32_e32 v12, vcc, 0xc000000, v10
	s_nop 1
	v_addc_co_u32_e32 v13, vcc, 0, v11, vcc
	v_add_co_u32_e32 v10, vcc, s1, v10
	s_nop 1
	v_addc_co_u32_e32 v11, vcc, 0, v11, vcc
	global_load_ushort v42, v[12:13], off offset:512
	global_load_ushort v43, v[12:13], off offset:1536
	global_load_ushort v44, v[12:13], off offset:2560
	global_load_ushort v45, v[12:13], off offset:3584
	global_load_ushort v46, v[10:11], off offset:512
	global_load_ushort v47, v[10:11], off offset:1536
	global_load_ushort v52, v[10:11], off offset:2560
	global_load_ushort v53, v[10:11], off offset:3584
	ds_read_u16 v32, v23
	ds_read_u16 v33, v23 offset:512
	ds_read_u16 v34, v23 offset:1024
	ds_read_u16 v35, v23 offset:1536
	ds_read_u16 v36, v23 offset:2048
	ds_read_u16 v37, v23 offset:2560
	ds_read_u16 v38, v23 offset:3072
	ds_read_u16 v39, v23 offset:3584
	ds_read_u16 v162, v23 offset:32768
	ds_read_u16 v163, v23 offset:33280
	ds_read_u16 v164, v23 offset:33792
	ds_read_u16 v165, v23 offset:34304
	ds_read_u16 v166, v23 offset:34816
	ds_read_u16 v167, v23 offset:35328
	ds_read_u16 v168, v23 offset:35840
	ds_read_u16 v169, v23 offset:36352
	v_lshl_add_u64 v[6:7], v[2:3], 0, v[4:5]
	v_lshl_add_u64 v[2:3], v[2:3], 0, s[22:23]
	s_waitcnt vmcnt(15) lgkmcnt(7)
	v_lshlrev_b32_e32 v24, 16, v24
	v_lshlrev_b32_e32 v32, 16, v32
	v_lshlrev_b32_e32 v162, 16, v162
	v_mul_f32_e32 v14, 0x3d372713, v24
	v_add_f32_e32 v32, v32, v162
	v_mul_f32_e32 v14, v14, v24
	v_fma_f32 v14, v14, v24, v24
	v_mul_f32_e32 v14, 0x3f4c422a, v14
	v_add_f32_e32 v14, v14, v14
	v_mul_f32_e32 v14, 0x3fb8aa3b, v14
	v_exp_f32_e32 v14, v14
	v_mul_f32_e32 v24, 0.5, v24
	v_add_f32_e32 v14, 1.0, v14
	s_nop 0
	v_rcp_f32_e32 v15, v14
	s_nop 0
	v_mul_f32_e32 v14, 2.0, v15
	v_sub_f32_e32 v14, 1.0, v14
	v_add_f32_e32 v14, 1.0, v14
	v_mul_f32_e32 v24, v24, v14
	v_mul_f32_e32 v32, v32, v24
	v_cvt_pk_bf16_f32 v32, v32, v32
	global_store_short v[6:7], v32, off offset:-2048
	s_waitcnt vmcnt(15) lgkmcnt(6)
	v_lshlrev_b32_e32 v25, 16, v25
	v_lshlrev_b32_e32 v33, 16, v33
	v_lshlrev_b32_e32 v163, 16, v163
	v_mul_f32_e32 v20, 0x3d372713, v25
	v_add_f32_e32 v33, v33, v163
	v_mul_f32_e32 v20, v20, v25
	v_fma_f32 v20, v20, v25, v25
	v_mul_f32_e32 v20, 0x3f4c422a, v20
	v_add_f32_e32 v20, v20, v20
	v_mul_f32_e32 v20, 0x3fb8aa3b, v20
	v_exp_f32_e32 v20, v20
	v_mul_f32_e32 v25, 0.5, v25
	v_add_f32_e32 v20, 1.0, v20
	s_nop 0
	v_rcp_f32_e32 v21, v20
	s_nop 0
	v_mul_f32_e32 v20, 2.0, v21
	v_sub_f32_e32 v20, 1.0, v20
	v_add_f32_e32 v20, 1.0, v20
	v_mul_f32_e32 v25, v25, v20
	v_mul_f32_e32 v33, v33, v25
	v_cvt_pk_bf16_f32 v33, v33, v33
	global_store_short v[6:7], v33, off offset:-1536
	s_waitcnt vmcnt(15) lgkmcnt(5)
	v_lshlrev_b32_e32 v26, 16, v26
	v_lshlrev_b32_e32 v34, 16, v34
	v_lshlrev_b32_e32 v164, 16, v164
	v_mul_f32_e32 v14, 0x3d372713, v26
	v_add_f32_e32 v34, v34, v164
	v_mul_f32_e32 v14, v14, v26
	v_fma_f32 v14, v14, v26, v26
	v_mul_f32_e32 v14, 0x3f4c422a, v14
	v_add_f32_e32 v14, v14, v14
	v_mul_f32_e32 v14, 0x3fb8aa3b, v14
	v_exp_f32_e32 v14, v14
	v_mul_f32_e32 v26, 0.5, v26
	v_add_f32_e32 v14, 1.0, v14
	s_nop 0
	v_rcp_f32_e32 v15, v14
	s_nop 0
	v_mul_f32_e32 v14, 2.0, v15
	v_sub_f32_e32 v14, 1.0, v14
	v_add_f32_e32 v14, 1.0, v14
	v_mul_f32_e32 v26, v26, v14
	v_mul_f32_e32 v34, v34, v26
	v_cvt_pk_bf16_f32 v34, v34, v34
	global_store_short v[6:7], v34, off offset:-1024
	s_waitcnt vmcnt(15) lgkmcnt(4)
; __device__ __forceinline__ bf16_t f2bf(float f) { return (bf16_t)(cvt_pk_bf16(f, 0.f) & 0xffffu); }
; __device__ __forceinline__ float bf2f(bf16_t b) { return __uint_as_float(((unsigned)b) << 16); }
; __device__ __forceinline__ float geluf_(float x) { const float y = 0.7978845608028654f * (x + 0.044715f * x * x * x); const float t = 1.0f - 2.0f / (1.0f + __expf(2.0f * y)); return 0.5f * x * (1.0f + t); }
; template <bool FINAL>
; __device__ __forceinline__ void lru_item(const Ctx& C, int l, int item) {
;     ...
;         for (int k8 = 0; k8 < 4; ++k8) { bf16_t gv_[8];
; #pragma unroll
;             for (int k = 0; k < 8; ++k) gv_[k] = gp[(size_t)(zz * 32 + k8 * 8 + k) * 512];
; #pragma unroll
;             for (int k = 0; k < 8; ++k) { const int tl = zz * 32 + k8 * 8 + k; const float hs = bf2f(H0[tl * 256 + ch]) + bf2f(H1[tl * 256 + ch]);
;                 yb[(size_t)tl * 256] = f2bf(hs * geluf_(bf2f(gv_[k]))); } }
;     }
;     __syncthreads();
	v_lshlrev_b32_e32 v27, 16, v27
	v_lshlrev_b32_e32 v35, 16, v35
	v_lshlrev_b32_e32 v165, 16, v165
	v_mul_f32_e32 v20, 0x3d372713, v27
	v_add_f32_e32 v35, v35, v165
	v_mul_f32_e32 v20, v20, v27
	v_fma_f32 v20, v20, v27, v27
	v_mul_f32_e32 v20, 0x3f4c422a, v20
	v_add_f32_e32 v20, v20, v20
	v_mul_f32_e32 v20, 0x3fb8aa3b, v20
	v_exp_f32_e32 v20, v20
	v_mul_f32_e32 v27, 0.5, v27
	v_add_f32_e32 v20, 1.0, v20
	s_nop 0
	v_rcp_f32_e32 v21, v20
	s_nop 0
	v_mul_f32_e32 v20, 2.0, v21
	v_sub_f32_e32 v20, 1.0, v20
	v_add_f32_e32 v20, 1.0, v20
	v_mul_f32_e32 v27, v27, v20
	v_mul_f32_e32 v35, v35, v27
	v_cvt_pk_bf16_f32 v35, v35, v35
	global_store_short v[6:7], v35, off offset:-512
	s_waitcnt vmcnt(15) lgkmcnt(3)
	v_lshlrev_b32_e32 v28, 16, v28
	v_lshlrev_b32_e32 v36, 16, v36
	v_lshlrev_b32_e32 v166, 16, v166
	v_mul_f32_e32 v14, 0x3d372713, v28
	v_add_f32_e32 v36, v36, v166
	v_mul_f32_e32 v14, v14, v28
	v_fma_f32 v14, v14, v28, v28
	v_mul_f32_e32 v14, 0x3f4c422a, v14
	v_add_f32_e32 v14, v14, v14
	v_mul_f32_e32 v14, 0x3fb8aa3b, v14
	v_exp_f32_e32 v14, v14
	v_mul_f32_e32 v28, 0.5, v28
	v_add_f32_e32 v14, 1.0, v14
	s_nop 0
	v_rcp_f32_e32 v15, v14
	s_nop 0
	v_mul_f32_e32 v14, 2.0, v15
	v_sub_f32_e32 v14, 1.0, v14
	v_add_f32_e32 v14, 1.0, v14
	v_mul_f32_e32 v28, v28, v14
	v_mul_f32_e32 v36, v36, v28
	v_cvt_pk_bf16_f32 v36, v36, v36
	global_store_short v[6:7], v36, off
	s_waitcnt vmcnt(15) lgkmcnt(2)
	v_lshlrev_b32_e32 v29, 16, v29
	v_lshlrev_b32_e32 v37, 16, v37
	v_lshlrev_b32_e32 v167, 16, v167
	v_mul_f32_e32 v20, 0x3d372713, v29
	v_add_f32_e32 v37, v37, v167
	v_mul_f32_e32 v20, v20, v29
	v_fma_f32 v20, v20, v29, v29
	v_mul_f32_e32 v20, 0x3f4c422a, v20
	v_add_f32_e32 v20, v20, v20
	v_mul_f32_e32 v20, 0x3fb8aa3b, v20
	v_exp_f32_e32 v20, v20
	v_mul_f32_e32 v29, 0.5, v29
	v_add_f32_e32 v20, 1.0, v20
	s_nop 0
	v_rcp_f32_e32 v21, v20
	s_nop 0
	v_mul_f32_e32 v20, 2.0, v21
	v_sub_f32_e32 v20, 1.0, v20
	v_add_f32_e32 v20, 1.0, v20
	v_mul_f32_e32 v29, v29, v20
	v_mul_f32_e32 v37, v37, v29
	v_cvt_pk_bf16_f32 v37, v37, v37
	global_store_short v[6:7], v37, off offset:512
	s_waitcnt vmcnt(15) lgkmcnt(1)
	v_lshlrev_b32_e32 v30, 16, v30
	v_lshlrev_b32_e32 v38, 16, v38
	v_lshlrev_b32_e32 v168, 16, v168
	v_mul_f32_e32 v14, 0x3d372713, v30
	v_add_f32_e32 v38, v38, v168
	v_mul_f32_e32 v14, v14, v30
	v_fma_f32 v14, v14, v30, v30
	v_mul_f32_e32 v14, 0x3f4c422a, v14
	v_add_f32_e32 v14, v14, v14
	v_mul_f32_e32 v14, 0x3fb8aa3b, v14
	v_exp_f32_e32 v14, v14
	v_mul_f32_e32 v30, 0.5, v30
	v_add_f32_e32 v14, 1.0, v14
	s_nop 0
	v_rcp_f32_e32 v15, v14
	s_nop 0
	v_mul_f32_e32 v14, 2.0, v15
	v_sub_f32_e32 v14, 1.0, v14
	v_add_f32_e32 v14, 1.0, v14
	v_mul_f32_e32 v30, v30, v14
	v_mul_f32_e32 v38, v38, v30
	v_cvt_pk_bf16_f32 v38, v38, v38
	global_store_short v[6:7], v38, off offset:1024
	s_waitcnt vmcnt(15) lgkmcnt(0)
	v_lshlrev_b32_e32 v31, 16, v31
	v_lshlrev_b32_e32 v39, 16, v39
	v_lshlrev_b32_e32 v169, 16, v169
	v_mul_f32_e32 v20, 0x3d372713, v31
	v_add_f32_e32 v39, v39, v169
	v_mul_f32_e32 v20, v20, v31
	v_fma_f32 v20, v20, v31, v31
	v_mul_f32_e32 v20, 0x3f4c422a, v20
	v_add_f32_e32 v20, v20, v20
	v_mul_f32_e32 v20, 0x3fb8aa3b, v20
	v_exp_f32_e32 v20, v20
	v_mul_f32_e32 v31, 0.5, v31
	v_add_f32_e32 v20, 1.0, v20
	s_nop 0
	v_rcp_f32_e32 v21, v20
	s_nop 0
	v_mul_f32_e32 v20, 2.0, v21
	v_sub_f32_e32 v20, 1.0, v20
	v_add_f32_e32 v20, 1.0, v20
	v_mul_f32_e32 v31, v31, v20
	v_mul_f32_e32 v39, v39, v31
	v_cvt_pk_bf16_f32 v39, v39, v39
	global_store_short v[6:7], v39, off offset:1536
	s_addk_i32 s0, 0x1000
	s_cmpk_lg_i32 s0, 0x4000
	s_waitcnt vmcnt(8)
	v_mov_b32_e32 v24, v42
	v_mov_b32_e32 v25, v43
	v_mov_b32_e32 v26, v44
	v_mov_b32_e32 v27, v45
	v_mov_b32_e32 v28, v46
	v_mov_b32_e32 v29, v47
	v_mov_b32_e32 v30, v52
	v_mov_b32_e32 v31, v53
	s_cbranch_scc1 .LBB0_683
	v_readlane_b32 s0, v254, 27
	s_add_i32 s48, s48, s26
	s_add_i32 s47, s47, s26
	s_add_i32 s46, s46, s0
	s_cmpk_gt_i32 s48, 0x1ff
	s_barrier
	s_cbranch_scc0 .LBB0_650
